# mlstmA pipelining extended: conv weights/bias of the next item also prefetched after conv compute
# baseline (speedup 1.0000x reference)
; DI void conv_unit(const u16* __restrict__ PM, const float* __restrict__ conv_w, const float* __restrict__ conv_b, int b, int sl0, int ch, float scale, float* a8) {
;   { const float4 b0 = *(const float4*)(conv_b + ch), b1 = *(const float4*)(conv_b + ch + 4); a8[0] = b0.x; a8[1] = b0.y; a8[2] = b0.z; a8[3] = b0.w; a8[4] = b1.x; a8[5] = b1.y; a8[6] = b1.z; a8[7] = b1.w; }
; #pragma unroll
;   for (int j = 0; j < 4; ++j) {
;     const int sl = sl0 - 3 + j;
;     if (sl >= 0) {
;       const uint4 raw = *(const uint4*)(PM + ((size_t)b * SEQ + sl) * 1024 + ch);
;       float x8[8]; unpack8(raw, x8);
;       const float4 w0 = *(const float4*)(conv_w + j * 1024 + ch), w1 = *(const float4*)(conv_w + j * 1024 + ch + 4);
;       a8[0] += w0.x * x8[0]; a8[1] += w0.y * x8[1]; a8[2] += w0.z * x8[2]; a8[3] += w0.w * x8[3];
;       a8[4] += w1.x * x8[4]; a8[5] += w1.y * x8[5]; a8[6] += w1.z * x8[6]; a8[7] += w1.w * x8[7];
;     }
;   }
; DI void mlstmA_item(const Params& p, char* lds, int item) {
;     ...
;   for (int i = 0; i < 2; ++i) {
;     const int q = tid + 512 * i, e = q >> 3, s8 = (q & 7) * 8;
;     *(uint4*)(VTs + e * 72 + s8) = *(const uint4*)(VTm + ((size_t)(bh * 128 + e)) * SEQ + c * 64 + s8);
;   }
.Lmg_next:
	s_add_i32 s80, s80, 1
	s_cmp_lt_u32 s80, 2
	s_cbranch_scc1 .Lmg_round
	s_mov_b32 s10, s94
	s_mov_b32 s96, 0
	v_add_u32_e32 v240, 0x200, v222
	s_and_b32 s73, s10, 0xffffff80
	v_lshlrev_b32_e32 v241, 4, v222
	v_ashrrev_i32_e32 v242, 3, v222
	v_ashrrev_i32_e32 v244, 3, v240
	v_and_b32_e32 v246, 0x70, v241
	v_mov_b32_e32 v247, 0
	v_add_u32_e32 v242, s73, v242
	v_add_u32_e32 v244, s73, v244
	s_and_b32 s78, s10, 0x7f
	s_lshl_b32 s78, s78, 7
	v_mov_b32_e32 v248, s78
	v_mov_b32_e32 v249, 0
	v_lshl_add_u64 v[248:249], s[6:7], 0, v[248:249]
	v_lshl_add_u64 v[248:249], v[248:249], 0, v[246:247]
	v_ashrrev_i32_e32 v243, 31, v242
	v_ashrrev_i32_e32 v245, 31, v244
	v_lshlrev_b64 v[242:243], 14, v[242:243]
	v_lshlrev_b64 v[244:245], 14, v[244:245]
	v_lshl_add_u64 v[242:243], v[248:249], 0, v[242:243]
	v_lshl_add_u64 v[244:245], v[248:249], 0, v[244:245]
	global_load_dwordx4 v[232:235], v[242:243], off
	global_load_dwordx4 v[236:239], v[244:245], off
	v_and_b32_e32 v70, 15, v222
	s_bfe_u32 s72, s10, 0x20007
	v_lshlrev_b32_e32 v70, 3, v70
	s_lshl_b32 s72, s72, 7
	v_add_u32_e32 v70, s72, v70
	v_lshlrev_b32_e32 v71, 2, v70
	v_add_u32_e32 v72, 0x1000, v71
	v_add_u32_e32 v73, 0x2000, v71
	v_add_u32_e32 v74, 0x3000, v71
	global_load_dwordx4 v[140:143], v71, s[62:63] offset:2048
	global_load_dwordx4 v[144:147], v71, s[62:63] offset:2064
	global_load_dwordx4 v[148:151], v72, s[62:63] offset:2048
	global_load_dwordx4 v[152:155], v72, s[62:63] offset:2064
	global_load_dwordx4 v[156:159], v73, s[62:63] offset:2048
	global_load_dwordx4 v[160:163], v73, s[62:63] offset:2064
	global_load_dwordx4 v[164:167], v74, s[62:63] offset:2048
	global_load_dwordx4 v[168:171], v74, s[62:63] offset:2064
	global_load_dwordx4 v[224:227], v71, s[64:65] offset:2048
	global_load_dwordx4 v[228:231], v71, s[64:65] offset:2064
	v_and_b32_e32 v70, 15, v222
	s_bfe_u32 s72, s10, 0x20007
	v_lshlrev_b32_e32 v70, 3, v70
	s_lshl_b32 s72, s72, 7
	v_add_u32_e32 v70, s72, v70
	s_ashr_i32 s74, s10, 9
	s_ashr_i32 s75, s74, 31
	s_lshl_b64 s[74:75], s[74:75], 24
	s_add_u32 s74, s74, s4
	s_addc_u32 s75, s75, s5
	v_lshlrev_b32_e32 v76, 1, v70
	v_mov_b32_e32 v77, 0
	v_lshl_add_u64 v[78:79], s[74:75], 0, v[76:77]
	s_and_b32 s76, s10, 0x7f
	s_lshl_b32 s76, s76, 6
	v_lshrrev_b32_e32 v75, 4, v222
	s_movk_i32 s77, 0x800
	v_add_u32_e32 v184, s76, v75
	v_add_u32_e32 v185, -1, v184
	v_mov_b32_e32 v114, 0
	v_mov_b32_e32 v115, 0
	v_mov_b32_e32 v116, 0
	v_mov_b32_e32 v117, 0
	v_mov_b32_e32 v118, 0
	v_mov_b32_e32 v119, 0
	v_mov_b32_e32 v120, 0
	v_mov_b32_e32 v121, 0
	v_mov_b32_e32 v122, 0
	v_mov_b32_e32 v123, 0
	v_mov_b32_e32 v124, 0
	v_mov_b32_e32 v125, 0
	v_mad_i64_i32 v[186:187], s[88:89], v185, s77, v[78:79]
	v_cmp_lt_i32_e64 s[84:85], 2, v184
	s_and_saveexec_b64 s[86:87], s[84:85]
	global_load_dwordx4 v[114:117], v[186:187], off offset:-3072
	s_or_b64 exec, exec, s[86:87]
	v_cmp_lt_i32_e64 s[84:85], 1, v184
	s_and_saveexec_b64 s[86:87], s[84:85]
	global_load_dwordx4 v[118:121], v[186:187], off offset:-1024
	s_or_b64 exec, exec, s[86:87]
	v_cmp_lt_i32_e64 s[84:85], 0, v184
	s_and_saveexec_b64 s[86:87], s[84:85]
	global_load_dwordx4 v[122:125], v[186:187], off offset:1024
	s_or_b64 exec, exec, s[86:87]
	global_load_dwordx4 v[126:129], v[186:187], off offset:3072
	v_add_u32_e32 v184, 32, v184
	v_add_u32_e32 v185, -1, v184
	v_mov_b32_e32 v130, 0
	v_mov_b32_e32 v131, 0
	v_mov_b32_e32 v132, 0
	v_mov_b32_e32 v133, 0
	v_mov_b32_e32 v134, 0
	v_mov_b32_e32 v135, 0
	v_mov_b32_e32 v136, 0
	v_mov_b32_e32 v137, 0
	v_mov_b32_e32 v172, 0
	v_mov_b32_e32 v173, 0
	v_mov_b32_e32 v174, 0
	v_mov_b32_e32 v175, 0
	v_mad_i64_i32 v[186:187], s[88:89], v185, s77, v[78:79]
	v_cmp_lt_i32_e64 s[84:85], 2, v184
	s_and_saveexec_b64 s[86:87], s[84:85]
	global_load_dwordx4 v[130:133], v[186:187], off offset:-3072
	s_or_b64 exec, exec, s[86:87]
	v_cmp_lt_i32_e64 s[84:85], 1, v184
	s_and_saveexec_b64 s[86:87], s[84:85]
	global_load_dwordx4 v[134:137], v[186:187], off offset:-1024
	s_or_b64 exec, exec, s[86:87]
	v_cmp_lt_i32_e64 s[84:85], 0, v184
	s_and_saveexec_b64 s[86:87], s[84:85]
	global_load_dwordx4 v[172:175], v[186:187], off offset:1024
	s_or_b64 exec, exec, s[86:87]
	global_load_dwordx4 v[176:179], v[186:187], off offset:3072
	s_waitcnt vmcnt(0)
	s_branch .LBB0_324

; DI u16 f2bf(float x) { return (u16)(pack2(x, 0.f) & 0xffffu); }
; DI void conv_unit(const u16* __restrict__ PM, const float* __restrict__ conv_w, const float* __restrict__ conv_b, int b, int sl0, int ch, float scale, float* a8) {
;   { const float4 b0 = *(const float4*)(conv_b + ch), b1 = *(const float4*)(conv_b + ch + 4); a8[0] = b0.x; a8[1] = b0.y; a8[2] = b0.z; a8[3] = b0.w; a8[4] = b1.x; a8[5] = b1.y; a8[6] = b1.z; a8[7] = b1.w; }
; #pragma unroll
;   for (int j = 0; j < 4; ++j) {
;     const int sl = sl0 - 3 + j;
;     if (sl >= 0) {
;       const uint4 raw = *(const uint4*)(PM + ((size_t)b * SEQ + sl) * 1024 + ch);
;       float x8[8]; unpack8(raw, x8);
;       const float4 w0 = *(const float4*)(conv_w + j * 1024 + ch), w1 = *(const float4*)(conv_w + j * 1024 + ch + 4);
;       a8[0] += w0.x * x8[0]; a8[1] += w0.y * x8[1]; a8[2] += w0.z * x8[2]; a8[3] += w0.w * x8[3];
;       a8[4] += w1.x * x8[4]; a8[5] += w1.y * x8[5]; a8[6] += w1.z * x8[6]; a8[7] += w1.w * x8[7];
;     }
;   }
; #pragma unroll
;   for (int e = 0; e < 8; ++e) { const float v = a8[e]; a8[e] = scale * v * __builtin_amdgcn_rcpf(1.f + __expf(-v)); }
; DI void mlstmA_item(const Params& p, char* lds, int item) {
;     ...
;   for (int i = 0; i < 2; ++i) {
;     const int q = tid + 512 * i, e = q >> 3, s8 = (q & 7) * 8;
;     *(uint4*)(VTs + e * 72 + s8) = *(const uint4*)(VTm + ((size_t)(bh * 128 + e)) * SEQ + c * 64 + s8);
;   }
;   __syncthreads();
; #pragma unroll 1
;   for (int i = 0; i < 2; ++i) {
;     const int cgk = tid & 15, t = (tid >> 4) + 32 * i;
;     float a8[8];
;     conv_unit(PM, p.in[5], p.in[6], b, c * 64 + t, 512 + hd * 128 + cgk * 8, 0.08838834764831845f, a8);
;     const float w = win[t];
; #pragma unroll
;     for (int e = 0; e < 8; ++e) KTs[(cgk * 8 + e) * 72 + t] = f2bf(a8[e] * w);
.LBB0_324:
	v_mov_b32_e32 v18, v222
	s_and_b32 s18, s10, 0x7f
	s_ashr_i32 s12, s10, 9
	s_nop 0
	v_cmp_lt_u32_e32 vcc, 63, v18
	s_and_saveexec_b64 s[0:1], vcc
	s_xor_b64 s[0:1], exec, s[0:1]
	s_lshl_b32 s8, s18, 6
	s_ashr_i32 s13, s12, 31
	s_or_saveexec_b64 s[14:15], s[0:1]
	s_bfe_u32 s27, s10, 0x20007
	v_and_b32_e32 v19, 63, v18
	s_ashr_i32 s11, s10, 31
	v_mov_b64_e32 v[10:11], s[12:13]
	v_mov_b64_e32 v[0:1], s[8:9]
	v_mov_b32_e32 v50, s8
.LBB0_330:
	s_or_b64 exec, exec, s[14:15]
	v_add_u32_e32 v4, 0x200, v18
	s_and_b32 s0, s10, 0xffffff80
	v_lshlrev_b32_e32 v2, 4, v18
	v_ashrrev_i32_e32 v9, 3, v18
	v_ashrrev_i32_e32 v14, 3, v4
	v_and_b32_e32 v16, 0x70, v2
	v_add_u32_e32 v2, s0, v9
	v_add_u32_e32 v4, s0, v14
	v_lshl_add_u64 v[0:1], v[0:1], 1, s[6:7]
	v_ashrrev_i32_e32 v3, 31, v2
	v_ashrrev_i32_e32 v5, 31, v4
	v_lshl_add_u64 v[0:1], v[0:1], 0, v[16:17]
	v_lshlrev_b64 v[2:3], 14, v[2:3]
	v_lshlrev_b64 v[4:5], 14, v[4:5]
	v_lshl_add_u64 v[2:3], v[0:1], 0, v[2:3]
	v_lshl_add_u64 v[4:5], v[0:1], 0, v[4:5]
	v_lshlrev_b32_e32 v8, 3, v18
	v_and_b32_e32 v22, 0x78, v8
	v_add_u32_e32 v8, 0, v16
	v_lshl_or_b32 v15, s27, 7, v22
	v_mad_u64_u32 v[12:13], s[0:1], v9, s26, v[8:9]
	v_lshlrev_b32_e32 v16, 2, v15
	v_mad_u64_u32 v[8:9], s[0:1], v14, s26, v[8:9]
	v_lshlrev_b64 v[10:11], 24, v[10:11]
	v_lshl_add_u64 v[10:11], s[4:5], 0, v[10:11]
	v_mov_b32_e32 v13, v17
	s_mov_b64 s[0:1], 0x1800
	v_ashrrev_i32_e32 v51, 4, v18
	v_mad_u32_u24 v52, v22, s26, 0
	s_mov_b32 s8, 0
	s_waitcnt vmcnt(20)
	ds_write_b128 v12, v[232:235] offset:18432
	ds_write_b128 v8, v[236:239] offset:18432
	s_waitcnt lgkmcnt(0)
	s_barrier
	s_add_i32 s97, s10, s70
	v_add_u32_e32 v240, 0x200, v222
	s_and_b32 s73, s97, 0xffffff80
	v_lshlrev_b32_e32 v241, 4, v222
	v_ashrrev_i32_e32 v242, 3, v222
	v_ashrrev_i32_e32 v244, 3, v240
	v_and_b32_e32 v246, 0x70, v241
	v_mov_b32_e32 v247, 0
	v_add_u32_e32 v242, s73, v242
	v_add_u32_e32 v244, s73, v244
	s_and_b32 s78, s97, 0x7f
	s_lshl_b32 s78, s78, 7
	v_mov_b32_e32 v248, s78
	v_mov_b32_e32 v249, 0
	v_lshl_add_u64 v[248:249], s[6:7], 0, v[248:249]
	v_lshl_add_u64 v[248:249], v[248:249], 0, v[246:247]
	v_ashrrev_i32_e32 v243, 31, v242
	v_ashrrev_i32_e32 v245, 31, v244
	v_lshlrev_b64 v[242:243], 14, v[242:243]
	v_lshlrev_b64 v[244:245], 14, v[244:245]
	v_lshl_add_u64 v[242:243], v[248:249], 0, v[242:243]
	v_lshl_add_u64 v[244:245], v[248:249], 0, v[244:245]
	global_load_dwordx4 v[232:235], v[242:243], off
	global_load_dwordx4 v[236:239], v[244:245], off
	s_waitcnt vmcnt(2)
	v_mov_b32_e32 v197, v51
	v_lshl_add_u32 v196, v197, 2, s96
	ds_read_b32 v196, v196 offset:40960
	v_lshl_add_u32 v198, v197, 1, v52
	v_lshlrev_b32_e32 v188, 16, v114
	v_and_b32_e32 v189, 0xffff0000, v114
	v_lshlrev_b32_e32 v190, 16, v115
	v_and_b32_e32 v191, 0xffff0000, v115
	v_lshlrev_b32_e32 v192, 16, v116
	v_and_b32_e32 v193, 0xffff0000, v116
	v_lshlrev_b32_e32 v194, 16, v117
	v_and_b32_e32 v195, 0xffff0000, v117
	v_pk_fma_f32 v[204:205], v[140:141], v[188:189], v[224:225]
	v_pk_fma_f32 v[206:207], v[142:143], v[190:191], v[226:227]
	v_pk_fma_f32 v[208:209], v[144:145], v[192:193], v[228:229]
	v_pk_fma_f32 v[210:211], v[146:147], v[194:195], v[230:231]
	v_lshlrev_b32_e32 v188, 16, v118
	v_and_b32_e32 v189, 0xffff0000, v118
	v_lshlrev_b32_e32 v190, 16, v119
	v_and_b32_e32 v191, 0xffff0000, v119
	v_lshlrev_b32_e32 v192, 16, v120
	v_and_b32_e32 v193, 0xffff0000, v120
	v_lshlrev_b32_e32 v194, 16, v121
	v_and_b32_e32 v195, 0xffff0000, v121
	v_pk_fma_f32 v[204:205], v[148:149], v[188:189], v[204:205]
	v_pk_fma_f32 v[206:207], v[150:151], v[190:191], v[206:207]
	v_pk_fma_f32 v[208:209], v[152:153], v[192:193], v[208:209]
	v_pk_fma_f32 v[210:211], v[154:155], v[194:195], v[210:211]
	v_lshlrev_b32_e32 v188, 16, v122
	v_and_b32_e32 v189, 0xffff0000, v122
	v_lshlrev_b32_e32 v190, 16, v123
	v_and_b32_e32 v191, 0xffff0000, v123
	v_lshlrev_b32_e32 v192, 16, v124
	v_and_b32_e32 v193, 0xffff0000, v124
	v_lshlrev_b32_e32 v194, 16, v125
	v_and_b32_e32 v195, 0xffff0000, v125
	v_pk_fma_f32 v[204:205], v[156:157], v[188:189], v[204:205]
	v_pk_fma_f32 v[206:207], v[158:159], v[190:191], v[206:207]
	v_pk_fma_f32 v[208:209], v[160:161], v[192:193], v[208:209]
	v_pk_fma_f32 v[210:211], v[162:163], v[194:195], v[210:211]
	v_lshlrev_b32_e32 v188, 16, v126
	v_and_b32_e32 v189, 0xffff0000, v126
	v_lshlrev_b32_e32 v190, 16, v127
	v_and_b32_e32 v191, 0xffff0000, v127
	v_lshlrev_b32_e32 v192, 16, v128
	v_and_b32_e32 v193, 0xffff0000, v128
	v_lshlrev_b32_e32 v194, 16, v129
	v_and_b32_e32 v195, 0xffff0000, v129
	v_pk_fma_f32 v[204:205], v[164:165], v[188:189], v[204:205]
	v_pk_fma_f32 v[206:207], v[166:167], v[190:191], v[206:207]
	v_pk_fma_f32 v[208:209], v[168:169], v[192:193], v[208:209]
	v_pk_fma_f32 v[210:211], v[170:171], v[194:195], v[210:211]
	v_mul_f32_e32 v212, 0xbfb8aa3b, v204
	v_mul_f32_e32 v213, 0xbfb8aa3b, v205
	v_mul_f32_e32 v214, 0xbfb8aa3b, v206
	v_mul_f32_e32 v215, 0xbfb8aa3b, v207
	v_mul_f32_e32 v216, 0xbfb8aa3b, v208
	v_mul_f32_e32 v217, 0xbfb8aa3b, v209
	v_mul_f32_e32 v218, 0xbfb8aa3b, v210
	v_mul_f32_e32 v219, 0xbfb8aa3b, v211
	v_mul_f32_e32 v188, 0x3db504f3, v204
	v_mul_f32_e32 v189, 0x3db504f3, v205
	v_mul_f32_e32 v190, 0x3db504f3, v206
	v_mul_f32_e32 v191, 0x3db504f3, v207
	v_mul_f32_e32 v192, 0x3db504f3, v208
	v_mul_f32_e32 v193, 0x3db504f3, v209
	v_mul_f32_e32 v194, 0x3db504f3, v210
	v_mul_f32_e32 v195, 0x3db504f3, v211
	v_exp_f32_e32 v212, v212
	v_exp_f32_e32 v213, v213
	v_exp_f32_e32 v214, v214
	v_exp_f32_e32 v215, v215
	v_exp_f32_e32 v216, v216
	v_exp_f32_e32 v217, v217
	v_exp_f32_e32 v218, v218
	v_exp_f32_e32 v219, v219
	v_add_f32_e32 v212, 1.0, v212
	v_add_f32_e32 v213, 1.0, v213
	v_add_f32_e32 v214, 1.0, v214
	v_add_f32_e32 v215, 1.0, v215
	v_add_f32_e32 v216, 1.0, v216
	v_add_f32_e32 v217, 1.0, v217
	v_add_f32_e32 v218, 1.0, v218
	v_add_f32_e32 v219, 1.0, v219
	v_rcp_f32_e32 v212, v212
	v_rcp_f32_e32 v213, v213
	v_rcp_f32_e32 v214, v214
	v_rcp_f32_e32 v215, v215
	v_rcp_f32_e32 v216, v216
	v_rcp_f32_e32 v217, v217
	v_rcp_f32_e32 v218, v218
	v_rcp_f32_e32 v219, v219
	v_mul_f32_e32 v188, v188, v212
	v_mul_f32_e32 v189, v189, v213
	v_mul_f32_e32 v190, v190, v214
	v_mul_f32_e32 v191, v191, v215
	v_mul_f32_e32 v192, v192, v216
	v_mul_f32_e32 v193, v193, v217
	v_mul_f32_e32 v194, v194, v218
	v_mul_f32_e32 v195, v195, v219
	s_waitcnt lgkmcnt(0)
; DI u16 f2bf(float x) { return (u16)(pack2(x, 0.f) & 0xffffu); }
; DI void conv_unit(const u16* __restrict__ PM, const float* __restrict__ conv_w, const float* __restrict__ conv_b, int b, int sl0, int ch, float scale, float* a8) {
;     ...
;   for (int j = 0; j < 4; ++j) {
;     const int sl = sl0 - 3 + j;
;     if (sl >= 0) {
;       const uint4 raw = *(const uint4*)(PM + ((size_t)b * SEQ + sl) * 1024 + ch);
;       float x8[8]; unpack8(raw, x8);
;       const float4 w0 = *(const float4*)(conv_w + j * 1024 + ch), w1 = *(const float4*)(conv_w + j * 1024 + ch + 4);
;       a8[0] += w0.x * x8[0]; a8[1] += w0.y * x8[1]; a8[2] += w0.z * x8[2]; a8[3] += w0.w * x8[3];
;       a8[4] += w1.x * x8[4]; a8[5] += w1.y * x8[5]; a8[6] += w1.z * x8[6]; a8[7] += w1.w * x8[7];
;     }
;   }
; #pragma unroll
;   for (int e = 0; e < 8; ++e) { const float v = a8[e]; a8[e] = scale * v * __builtin_amdgcn_rcpf(1.f + __expf(-v)); }
; DI void mlstmA_item(const Params& p, char* lds, int item) {
;     ...
;   for (int i = 0; i < 2; ++i) {
;     const int cgk = tid & 15, t = (tid >> 4) + 32 * i;
;     float a8[8];
;     conv_unit(PM, p.in[5], p.in[6], b, c * 64 + t, 512 + hd * 128 + cgk * 8, 0.08838834764831845f, a8);
;     const float w = win[t];
; #pragma unroll
;     for (int e = 0; e < 8; ++e) KTs[(cgk * 8 + e) * 72 + t] = f2bf(a8[e] * w);
	v_mul_f32_e32 v188, v196, v188
	v_mul_f32_e32 v189, v196, v189
	v_mul_f32_e32 v190, v196, v190
	v_mul_f32_e32 v191, v196, v191
	v_mul_f32_e32 v192, v196, v192
	v_mul_f32_e32 v193, v196, v193
	v_mul_f32_e32 v194, v196, v194
	v_mul_f32_e32 v195, v196, v195
	v_cvt_pk_bf16_f32 v188, v188, s77
	v_cvt_pk_bf16_f32 v189, v189, s77
	v_cvt_pk_bf16_f32 v190, v190, s77
	v_cvt_pk_bf16_f32 v191, v191, s77
	v_cvt_pk_bf16_f32 v192, v192, s77
	v_cvt_pk_bf16_f32 v193, v193, s77
	v_cvt_pk_bf16_f32 v194, v194, s77
	v_cvt_pk_bf16_f32 v195, v195, s77
	ds_write_b16 v198, v188
	ds_write_b16 v198, v189 offset:144
	ds_write_b16 v198, v190 offset:288
	ds_write_b16 v198, v191 offset:432
	ds_write_b16 v198, v192 offset:576
	ds_write_b16 v198, v193 offset:720
	ds_write_b16 v198, v194 offset:864
	ds_write_b16 v198, v195 offset:1008
	v_add_u32_e32 v197, 32, v51
	v_lshl_add_u32 v196, v197, 2, s96
	ds_read_b32 v196, v196 offset:40960
	v_lshl_add_u32 v198, v197, 1, v52
	v_lshlrev_b32_e32 v188, 16, v130
	v_and_b32_e32 v189, 0xffff0000, v130
	v_lshlrev_b32_e32 v190, 16, v131
	v_and_b32_e32 v191, 0xffff0000, v131
	v_lshlrev_b32_e32 v192, 16, v132
	v_and_b32_e32 v193, 0xffff0000, v132
	v_lshlrev_b32_e32 v194, 16, v133
	v_and_b32_e32 v195, 0xffff0000, v133
	v_pk_fma_f32 v[204:205], v[140:141], v[188:189], v[224:225]
	v_pk_fma_f32 v[206:207], v[142:143], v[190:191], v[226:227]
	v_pk_fma_f32 v[208:209], v[144:145], v[192:193], v[228:229]
	v_pk_fma_f32 v[210:211], v[146:147], v[194:195], v[230:231]
	v_lshlrev_b32_e32 v188, 16, v134
	v_and_b32_e32 v189, 0xffff0000, v134
	v_lshlrev_b32_e32 v190, 16, v135
	v_and_b32_e32 v191, 0xffff0000, v135
	v_lshlrev_b32_e32 v192, 16, v136
	v_and_b32_e32 v193, 0xffff0000, v136
	v_lshlrev_b32_e32 v194, 16, v137
	v_and_b32_e32 v195, 0xffff0000, v137
	v_pk_fma_f32 v[204:205], v[148:149], v[188:189], v[204:205]
	v_pk_fma_f32 v[206:207], v[150:151], v[190:191], v[206:207]
	v_pk_fma_f32 v[208:209], v[152:153], v[192:193], v[208:209]
	v_pk_fma_f32 v[210:211], v[154:155], v[194:195], v[210:211]
	v_lshlrev_b32_e32 v188, 16, v172
	v_and_b32_e32 v189, 0xffff0000, v172
	v_lshlrev_b32_e32 v190, 16, v173
	v_and_b32_e32 v191, 0xffff0000, v173
	v_lshlrev_b32_e32 v192, 16, v174
	v_and_b32_e32 v193, 0xffff0000, v174
	v_lshlrev_b32_e32 v194, 16, v175
	v_and_b32_e32 v195, 0xffff0000, v175
	v_pk_fma_f32 v[204:205], v[156:157], v[188:189], v[204:205]
	v_pk_fma_f32 v[206:207], v[158:159], v[190:191], v[206:207]
	v_pk_fma_f32 v[208:209], v[160:161], v[192:193], v[208:209]
	v_pk_fma_f32 v[210:211], v[162:163], v[194:195], v[210:211]
	v_lshlrev_b32_e32 v188, 16, v176
	v_and_b32_e32 v189, 0xffff0000, v176
	v_lshlrev_b32_e32 v190, 16, v177
	v_and_b32_e32 v191, 0xffff0000, v177
	v_lshlrev_b32_e32 v192, 16, v178
	v_and_b32_e32 v193, 0xffff0000, v178
	v_lshlrev_b32_e32 v194, 16, v179
	v_and_b32_e32 v195, 0xffff0000, v179
	v_pk_fma_f32 v[204:205], v[164:165], v[188:189], v[204:205]
	v_pk_fma_f32 v[206:207], v[166:167], v[190:191], v[206:207]
	v_pk_fma_f32 v[208:209], v[168:169], v[192:193], v[208:209]
	v_pk_fma_f32 v[210:211], v[170:171], v[194:195], v[210:211]
	v_mul_f32_e32 v212, 0xbfb8aa3b, v204
	v_mul_f32_e32 v213, 0xbfb8aa3b, v205
	v_mul_f32_e32 v214, 0xbfb8aa3b, v206
	v_mul_f32_e32 v215, 0xbfb8aa3b, v207
	v_mul_f32_e32 v216, 0xbfb8aa3b, v208
	v_mul_f32_e32 v217, 0xbfb8aa3b, v209
	v_mul_f32_e32 v218, 0xbfb8aa3b, v210
	v_mul_f32_e32 v219, 0xbfb8aa3b, v211
	v_mul_f32_e32 v188, 0x3db504f3, v204
	v_mul_f32_e32 v189, 0x3db504f3, v205
	v_mul_f32_e32 v190, 0x3db504f3, v206
	v_mul_f32_e32 v191, 0x3db504f3, v207
	v_mul_f32_e32 v192, 0x3db504f3, v208
	v_mul_f32_e32 v193, 0x3db504f3, v209
	v_mul_f32_e32 v194, 0x3db504f3, v210
	v_mul_f32_e32 v195, 0x3db504f3, v211
	v_exp_f32_e32 v212, v212
	v_exp_f32_e32 v213, v213
	v_exp_f32_e32 v214, v214
	v_exp_f32_e32 v215, v215
	v_exp_f32_e32 v216, v216
	v_exp_f32_e32 v217, v217
	v_exp_f32_e32 v218, v218
	v_exp_f32_e32 v219, v219
	v_add_f32_e32 v212, 1.0, v212
	v_add_f32_e32 v213, 1.0, v213
	v_add_f32_e32 v214, 1.0, v214
	v_add_f32_e32 v215, 1.0, v215
	v_add_f32_e32 v216, 1.0, v216
	v_add_f32_e32 v217, 1.0, v217
	v_add_f32_e32 v218, 1.0, v218
	v_add_f32_e32 v219, 1.0, v219
	v_rcp_f32_e32 v212, v212
	v_rcp_f32_e32 v213, v213
	v_rcp_f32_e32 v214, v214
	v_rcp_f32_e32 v215, v215
	v_rcp_f32_e32 v216, v216
	v_rcp_f32_e32 v217, v217
	v_rcp_f32_e32 v218, v218
	v_rcp_f32_e32 v219, v219
	v_mul_f32_e32 v188, v188, v212
	v_mul_f32_e32 v189, v189, v213
	v_mul_f32_e32 v190, v190, v214
	v_mul_f32_e32 v191, v191, v215
	v_mul_f32_e32 v192, v192, v216
	v_mul_f32_e32 v193, v193, v217
	v_mul_f32_e32 v194, v194, v218
	v_mul_f32_e32 v195, v195, v219
	s_waitcnt lgkmcnt(0)
; DI u16 f2bf(float x) { return (u16)(pack2(x, 0.f) & 0xffffu); }
; DI void conv_unit(const u16* __restrict__ PM, const float* __restrict__ conv_w, const float* __restrict__ conv_b, int b, int sl0, int ch, float scale, float* a8) {
;   { const float4 b0 = *(const float4*)(conv_b + ch), b1 = *(const float4*)(conv_b + ch + 4); a8[0] = b0.x; a8[1] = b0.y; a8[2] = b0.z; a8[3] = b0.w; a8[4] = b1.x; a8[5] = b1.y; a8[6] = b1.z; a8[7] = b1.w; }
; #pragma unroll
;   for (int j = 0; j < 4; ++j) {
;     const int sl = sl0 - 3 + j;
;     if (sl >= 0) {
;       const uint4 raw = *(const uint4*)(PM + ((size_t)b * SEQ + sl) * 1024 + ch);
;       float x8[8]; unpack8(raw, x8);
;       const float4 w0 = *(const float4*)(conv_w + j * 1024 + ch), w1 = *(const float4*)(conv_w + j * 1024 + ch + 4);
;       a8[0] += w0.x * x8[0]; a8[1] += w0.y * x8[1]; a8[2] += w0.z * x8[2]; a8[3] += w0.w * x8[3];
;       a8[4] += w1.x * x8[4]; a8[5] += w1.y * x8[5]; a8[6] += w1.z * x8[6]; a8[7] += w1.w * x8[7];
;     }
;   }
; DI void mlstmA_item(const Params& p, char* lds, int item) {
;     ...
;     const float w = win[t];
; #pragma unroll
;     for (int e = 0; e < 8; ++e) KTs[(cgk * 8 + e) * 72 + t] = f2bf(a8[e] * w);
	v_mul_f32_e32 v188, v196, v188
	v_mul_f32_e32 v189, v196, v189
	v_mul_f32_e32 v190, v196, v190
	v_mul_f32_e32 v191, v196, v191
	v_mul_f32_e32 v192, v196, v192
	v_mul_f32_e32 v193, v196, v193
	v_mul_f32_e32 v194, v196, v194
	v_mul_f32_e32 v195, v196, v195
	v_cvt_pk_bf16_f32 v188, v188, s77
	v_cvt_pk_bf16_f32 v189, v189, s77
	v_cvt_pk_bf16_f32 v190, v190, s77
	v_cvt_pk_bf16_f32 v191, v191, s77
	v_cvt_pk_bf16_f32 v192, v192, s77
	v_cvt_pk_bf16_f32 v193, v193, s77
	v_cvt_pk_bf16_f32 v194, v194, s77
	v_cvt_pk_bf16_f32 v195, v195, s77
	ds_write_b16 v198, v188
	ds_write_b16 v198, v189 offset:144
	ds_write_b16 v198, v190 offset:288
	ds_write_b16 v198, v191 offset:432
	ds_write_b16 v198, v192 offset:576
	ds_write_b16 v198, v193 offset:720
	ds_write_b16 v198, v194 offset:864
	ds_write_b16 v198, v195 offset:1008
	s_add_i32 s97, s10, s70
	v_and_b32_e32 v70, 15, v222
	s_bfe_u32 s72, s97, 0x20007
	v_lshlrev_b32_e32 v70, 3, v70
	s_lshl_b32 s72, s72, 7
	v_add_u32_e32 v70, s72, v70
	v_lshlrev_b32_e32 v71, 2, v70
	v_add_u32_e32 v72, 0x1000, v71
	v_add_u32_e32 v73, 0x2000, v71
	v_add_u32_e32 v74, 0x3000, v71
	global_load_dwordx4 v[140:143], v71, s[62:63] offset:2048
	global_load_dwordx4 v[144:147], v71, s[62:63] offset:2064
	global_load_dwordx4 v[148:151], v72, s[62:63] offset:2048
	global_load_dwordx4 v[152:155], v72, s[62:63] offset:2064
	global_load_dwordx4 v[156:159], v73, s[62:63] offset:2048
	global_load_dwordx4 v[160:163], v73, s[62:63] offset:2064
	global_load_dwordx4 v[164:167], v74, s[62:63] offset:2048
	global_load_dwordx4 v[168:171], v74, s[62:63] offset:2064
	global_load_dwordx4 v[224:227], v71, s[64:65] offset:2048
	global_load_dwordx4 v[228:231], v71, s[64:65] offset:2064
	v_and_b32_e32 v70, 15, v222
	s_bfe_u32 s72, s97, 0x20007
	v_lshlrev_b32_e32 v70, 3, v70
	s_lshl_b32 s72, s72, 7
	v_add_u32_e32 v70, s72, v70
	s_ashr_i32 s74, s97, 9
	s_ashr_i32 s75, s74, 31
	s_lshl_b64 s[74:75], s[74:75], 24
	s_add_u32 s74, s74, s4
	s_addc_u32 s75, s75, s5
	v_lshlrev_b32_e32 v76, 1, v70
	v_mov_b32_e32 v77, 0
	v_lshl_add_u64 v[78:79], s[74:75], 0, v[76:77]
	s_and_b32 s76, s97, 0x7f
	s_lshl_b32 s76, s76, 6
	v_lshrrev_b32_e32 v75, 4, v222
	s_movk_i32 s77, 0x800
	v_add_u32_e32 v184, s76, v75
	v_add_u32_e32 v185, -1, v184
	v_mov_b32_e32 v114, 0
	v_mov_b32_e32 v115, 0
	v_mov_b32_e32 v116, 0
	v_mov_b32_e32 v117, 0
	v_mov_b32_e32 v118, 0
	v_mov_b32_e32 v119, 0
	v_mov_b32_e32 v120, 0
	v_mov_b32_e32 v121, 0
	v_mov_b32_e32 v122, 0
	v_mov_b32_e32 v123, 0
	v_mov_b32_e32 v124, 0
	v_mov_b32_e32 v125, 0
	v_mad_i64_i32 v[186:187], s[88:89], v185, s77, v[78:79]
	v_cmp_lt_i32_e64 s[84:85], 2, v184
	s_and_saveexec_b64 s[86:87], s[84:85]
	global_load_dwordx4 v[114:117], v[186:187], off offset:-3072
	s_or_b64 exec, exec, s[86:87]
	v_cmp_lt_i32_e64 s[84:85], 1, v184
	s_and_saveexec_b64 s[86:87], s[84:85]
	global_load_dwordx4 v[118:121], v[186:187], off offset:-1024
	s_or_b64 exec, exec, s[86:87]
	v_cmp_lt_i32_e64 s[84:85], 0, v184
	s_and_saveexec_b64 s[86:87], s[84:85]
	global_load_dwordx4 v[122:125], v[186:187], off offset:1024
	s_or_b64 exec, exec, s[86:87]
	global_load_dwordx4 v[126:129], v[186:187], off offset:3072
	v_add_u32_e32 v184, 32, v184
	v_add_u32_e32 v185, -1, v184
	v_mov_b32_e32 v130, 0
	v_mov_b32_e32 v131, 0
	v_mov_b32_e32 v132, 0
	v_mov_b32_e32 v133, 0
	v_mov_b32_e32 v134, 0
	v_mov_b32_e32 v135, 0
	v_mov_b32_e32 v136, 0
	v_mov_b32_e32 v137, 0
	v_mov_b32_e32 v172, 0
	v_mov_b32_e32 v173, 0
	v_mov_b32_e32 v174, 0
	v_mov_b32_e32 v175, 0
	v_mad_i64_i32 v[186:187], s[88:89], v185, s77, v[78:79]
	v_cmp_lt_i32_e64 s[84:85], 2, v184
	s_and_saveexec_b64 s[86:87], s[84:85]
	global_load_dwordx4 v[130:133], v[186:187], off offset:-3072
	s_or_b64 exec, exec, s[86:87]
	v_cmp_lt_i32_e64 s[84:85], 1, v184
	s_and_saveexec_b64 s[86:87], s[84:85]
	global_load_dwordx4 v[134:137], v[186:187], off offset:-1024
	s_or_b64 exec, exec, s[86:87]
	v_cmp_lt_i32_e64 s[84:85], 0, v184
	s_and_saveexec_b64 s[86:87], s[84:85]
	global_load_dwordx4 v[172:175], v[186:187], off offset:1024
	s_or_b64 exec, exec, s[86:87]
	global_load_dwordx4 v[176:179], v[186:187], off offset:3072
